# dense attention: LDS-DMA issue block moved into the shadow of the first QK MFMAs (both head-dim variants), inactive waves issue it on a side path
# baseline (speedup 1.0000x reference)
; template <int DK, int QB, bool NA>
; DEVI void attn_item(const AttnArgs& a, unsigned char* smem) {
;     ...
;   for (int j = 0; j < nt; ++j) {
;     if (j + 1 < nt) {
;       if constexpr (DK == 96) asm volatile("s_waitcnt vmcnt(5)" ::: "memory");
;       else                    asm volatile("s_waitcnt vmcnt(4)" ::: "memory");
;     } else {
;       asm volatile("s_waitcnt vmcnt(0)" ::: "memory");
;     }
;     RAW_BARRIER();
;     if (j + 2 < nt) ATT_ISSUE(j + 2, is);
;     is = (is + 1 == S) ? 0 : is + 1;
;     const unsigned cur = lbase + cs * ATT_STAGE;
;     cs = (cs + 1 == S) ? 0 : cs + 1;
;     if (wact) {
;       f32x4 s[4][QB];
; #pragma unroll
;       for (int kb = 0; kb < 4; ++kb)
; #pragma unroll
;         for (int qb = 0; qb < QB; ++qb) s[kb][qb] = (f32x4){0.f, 0.f, 0.f, 0.f};
;       {
;         bf16x8 k0[4], k1[4], k2[4];
;         const unsigned a0 = cur + ka0, a1 = cur + ka1, a2 = cur + kr;
;         k0[0] = ldsr<0>(a0); k0[1] = ldsr<2048>(a0); k0[2] = ldsr<4096>(a0); k0[3] = ldsr<6144>(a0);
;         k1[0] = ldsr<0>(a1); k1[1] = ldsr<2048>(a1); k1[2] = ldsr<4096>(a1); k1[3] = ldsr<6144>(a1);
;         if constexpr (KS == 3) { k2[0] = ldsr<0>(a2); k2[1] = ldsr<1024>(a2); k2[2] = ldsr<2048>(a2); k2[3] = ldsr<3072>(a2); }
;         if constexpr (KS == 3) asm volatile("s_waitcnt lgkmcnt(8)" : "+v"(k0[0]), "+v"(k0[1]), "+v"(k0[2]), "+v"(k0[3]) :: "memory");
;         else                   asm volatile("s_waitcnt lgkmcnt(4)" : "+v"(k0[0]), "+v"(k0[1]), "+v"(k0[2]), "+v"(k0[3]) :: "memory");
;         __builtin_amdgcn_sched_barrier(0);
; #pragma unroll
;         for (int kb = 0; kb < 4; ++kb)
; #pragma unroll
;           for (int qb = 0; qb < QB; ++qb) s[kb][qb] = __builtin_amdgcn_mfma_f32_16x16x32_bf16(k0[kb], qf[qb][0], s[kb][qb], 0, 0, 0);
;         if constexpr (KS == 3) asm volatile("s_waitcnt lgkmcnt(4)" : "+v"(k1[0]), "+v"(k1[1]), "+v"(k1[2]), "+v"(k1[3]) :: "memory");
;         else                   asm volatile("s_waitcnt lgkmcnt(0)" : "+v"(k1[0]), "+v"(k1[1]), "+v"(k1[2]), "+v"(k1[3]) :: "memory");
;         __builtin_amdgcn_sched_barrier(0);
; #pragma unroll
;         for (int kb = 0; kb < 4; ++kb)
; #pragma unroll
;           for (int qb = 0; qb < QB; ++qb) s[kb][qb] = __builtin_amdgcn_mfma_f32_16x16x32_bf16(k1[kb], qf[qb][1], s[kb][qb], 0, 0, 0);
;         if constexpr (KS == 3) {
.LBB0_2269:
	s_add_i32 s9, s9, 1
	s_cmp_lt_u32 s9, s61
	s_cselect_b32 s20, s44, s60
	s_mul_i32 s40, s8, 0x5000
	v_add_u32_e32 v0, s40, v185
	v_mad_u64_u32 v[2:3], s[40:41], s20, v205, v[106:107]
	s_mov_b64 s[28:29], 0x700
	v_readfirstlane_b32 s40, v0
	s_mul_i32 s100, s3, 0x5000
	v_or_b32_e32 v208, s100, v183
	v_or_b32_e32 v209, s100, v184
	s_waitcnt vmcnt(4)
	v_lshl_add_u64 v[210:211], v[2:3], 0, s[28:29]
	s_mov_b32 m0, s40
	s_waitcnt lgkmcnt(0)
	s_barrier
	ds_read_b128 v[52:55], v208 offset:0
	ds_read_b128 v[56:59], v208 offset:0x800
	ds_read_b128 v[60:63], v208 offset:0x1000
	ds_read_b128 v[64:67], v208 offset:0x1800
	ds_read_b128 v[68:71], v209 offset:0
	ds_read_b128 v[72:75], v209 offset:0x800
	ds_read_b128 v[76:79], v209 offset:0x1000
	ds_read_b128 v[80:83], v209 offset:0x1800
	s_and_saveexec_b64 s[42:43], s[0:1]
	s_cbranch_execz .Lgq_dma_stub
	s_waitcnt lgkmcnt(4)
	s_setprio 1
	v_mfma_f32_16x16x32_bf16 v[84:87], v[52:55], v[16:19], 0
	global_load_lds_dwordx4 v[210:211], off
	v_add_u32_e32 v210, 0x1000, v0
	s_waitcnt lgkmcnt(0)
	v_mfma_f32_16x16x32_bf16 v[52:55], v[52:55], v[12:15], 0
	s_mov_b64 s[28:29], 0x10f00
	v_readfirstlane_b32 s40, v210
	v_add_u32_e32 v210, 0x3000, v0
	v_mfma_f32_16x16x32_bf16 v[88:91], v[56:59], v[16:19], 0
	v_lshl_add_u64 v[2:3], v[2:3], 0, s[28:29]
	s_mov_b32 m0, s40
	s_lshl_b64 s[40:41], s[20:21], 1
	v_mfma_f32_16x16x32_bf16 v[56:59], v[56:59], v[12:15], 0
	v_readfirstlane_b32 s20, v210
	v_add_u32_e32 v0, 0x4000, v0
	global_load_lds_dwordx4 v[2:3], off
	v_mfma_f32_16x16x32_bf16 v[110:113], v[60:63], v[16:19], 0
	v_lshl_add_u64 v[2:3], v[104:105], 0, s[40:41]
	s_mov_b32 m0, s20
	v_readfirstlane_b32 s20, v0
	v_mfma_f32_16x16x32_bf16 v[60:63], v[60:63], v[12:15], 0
	global_load_lds_dwordx4 v[2:3], off
	v_lshl_add_u64 v[2:3], v[108:109], 0, s[40:41]
	s_mov_b32 m0, s20
	v_mfma_f32_16x16x32_bf16 v[114:117], v[64:67], v[16:19], 0
	global_load_lds_dwordx4 v[2:3], off
	v_mfma_f32_16x16x32_bf16 v[64:67], v[64:67], v[12:15], 0
	v_mfma_f32_16x16x32_bf16 v[118:121], v[68:71], v[8:11], v[84:87]
	v_add_u32_e32 v0, s100, v129
	v_add_u32_e32 v2, s100, v180
	v_add_u32_e32 v3, s100, v181
	v_mfma_f32_16x16x32_bf16 v[208:211], v[72:75], v[8:11], v[88:91]
	v_mfma_f32_16x16x32_bf16 v[110:113], v[76:79], v[8:11], v[110:113]
	s_nop 2
	v_fma_f32 v120, v120, s92, -v102
	v_fma_f32 v121, v121, s92, -v102
	v_pk_fma_f32 v[122:123], v[118:119], s[92:93], v[102:103] op_sel_hi:[1,0,0] neg_lo:[0,0,1] neg_hi:[0,0,1]
	s_nop 0
	v_pk_fma_f32 v[118:119], v[210:211], s[92:93], v[102:103] op_sel_hi:[1,0,0] neg_lo:[0,0,1] neg_hi:[0,0,1]
	v_mfma_f32_16x16x32_bf16 v[212:215], v[80:83], v[8:11], v[114:117]
	v_max_f32_e32 v125, v118, v119
	v_pk_fma_f32 v[112:113], v[112:113], s[92:93], v[102:103] op_sel_hi:[1,0,0] neg_lo:[0,0,1] neg_hi:[0,0,1]
	v_mfma_f32_16x16x32_bf16 v[96:99], v[68:71], v[4:7], v[52:55]
	v_fma_f32 v116, v208, s92, -v102
	v_fma_f32 v117, v209, s92, -v102
	v_pk_fma_f32 v[114:115], v[110:111], s[92:93], v[102:103] op_sel_hi:[1,0,0] neg_lo:[0,0,1] neg_hi:[0,0,1]
	v_max_f32_e32 v124, v116, v117
	v_mfma_f32_16x16x32_bf16 v[92:95], v[72:75], v[4:7], v[56:59]
	v_add_u32_e32 v54, s100, v182
	v_pk_fma_f32 v[110:111], v[212:213], s[92:93], v[102:103] op_sel_hi:[1,0,0] neg_lo:[0,0,1] neg_hi:[0,0,1]
	s_mov_b32 s20, 0x40c00000
	v_mfma_f32_16x16x32_bf16 v[88:91], v[76:79], v[4:7], v[60:63]
	v_mfma_f32_16x16x32_bf16 v[84:87], v[80:83], v[4:7], v[64:67]
	s_setprio 0
	ds_read_b64 v[80:81], v0 offset:0
	ds_read_b64 v[82:83], v2 offset:0
	ds_read_b64 v[76:77], v0 offset:0x800
	ds_read_b64 v[78:79], v2 offset:0x800
	ds_read_b64 v[72:73], v0 offset:0x1000
	ds_read_b64 v[74:75], v2 offset:0x1000
	ds_read_b64 v[68:69], v0 offset:0x1800
	v_max_f32_e32 v0, v120, v121
	v_max3_f32 v0, v122, v123, v0
	ds_read_b64 v[70:71], v2 offset:0x1800
	ds_read_b64 v[64:65], v3 offset:0
	ds_read_b64 v[66:67], v54 offset:0
	ds_read_b64 v[60:61], v3 offset:0x800
	ds_read_b64 v[62:63], v54 offset:0x800
	ds_read_b64 v[56:57], v3 offset:0x1000
	ds_read_b64 v[58:59], v54 offset:0x1000
	ds_read_b64 v[52:53], v3 offset:0x1800
	v_pk_fma_f32 v[2:3], v[214:215], s[92:93], v[102:103] op_sel_hi:[1,0,0] neg_lo:[0,0,1] neg_hi:[0,0,1]
	v_max3_f32 v0, v0, v124, v125
	v_max_f32_e32 v124, v114, v115
	v_max_f32_e32 v125, v112, v113
	v_max3_f32 v0, v0, v124, v125
	v_max_f32_e32 v124, v110, v111
	v_max_f32_e32 v125, v2, v3
	v_max3_f32 v0, v0, v124, v125
	v_cmp_lt_f32_e32 vcc, s20, v0
	ds_read_b64 v[54:55], v54 offset:0x1800
	s_cbranch_vccz .LBB0_2272
	v_mov_b32_e32 v124, v0
	s_nop 1
	v_permlane16_swap_b32_e32 v0, v124
	v_max_f32_e32 v124, v124, v124
	v_max_f32_e32 v0, v0, v0
	v_max_f32_e32 v0, v0, v124
	v_mov_b32_e32 v124, v0
	s_nop 1
	v_permlane32_swap_b32_e32 v0, v124
	v_max3_f32 v0, v0, v124, 0
	v_exp_f32_e64 v124, -v0
	v_pk_add_f32 v[122:123], v[122:123], v[0:1] op_sel_hi:[1,0] neg_lo:[0,1] neg_hi:[0,1]
	v_pk_add_f32 v[120:121], v[120:121], v[0:1] op_sel_hi:[1,0] neg_lo:[0,1] neg_hi:[0,1]
	v_pk_add_f32 v[116:117], v[116:117], v[0:1] op_sel_hi:[1,0] neg_lo:[0,1] neg_hi:[0,1]
	v_pk_add_f32 v[118:119], v[118:119], v[0:1] op_sel_hi:[1,0] neg_lo:[0,1] neg_hi:[0,1]
	v_pk_add_f32 v[114:115], v[114:115], v[0:1] op_sel_hi:[1,0] neg_lo:[0,1] neg_hi:[0,1]
	v_pk_add_f32 v[112:113], v[112:113], v[0:1] op_sel_hi:[1,0] neg_lo:[0,1] neg_hi:[0,1]
	v_pk_add_f32 v[110:111], v[110:111], v[0:1] op_sel_hi:[1,0] neg_lo:[0,1] neg_hi:[0,1]
	v_pk_add_f32 v[2:3], v[2:3], v[0:1] op_sel_hi:[1,0] neg_lo:[0,1] neg_hi:[0,1]
	v_add_f32_e32 v102, v102, v0
	v_mul_f32_e32 v101, v101, v124
	v_pk_mul_f32 v[50:51], v[50:51], v[124:125] op_sel_hi:[1,0]
	v_pk_mul_f32 v[48:49], v[48:49], v[124:125] op_sel_hi:[1,0]
	v_pk_mul_f32 v[42:43], v[42:43], v[124:125] op_sel_hi:[1,0]
	v_pk_mul_f32 v[40:41], v[40:41], v[124:125] op_sel_hi:[1,0]
	v_pk_mul_f32 v[34:35], v[34:35], v[124:125] op_sel_hi:[1,0]
	v_pk_mul_f32 v[32:33], v[32:33], v[124:125] op_sel_hi:[1,0]
	v_pk_mul_f32 v[26:27], v[26:27], v[124:125] op_sel_hi:[1,0]
	v_pk_mul_f32 v[24:25], v[24:25], v[124:125] op_sel_hi:[1,0]

; template <int DK, int QB, bool NA>
; DEVI void attn_item(const AttnArgs& a, unsigned char* smem) {
;     ...
;     if (j + 2 < nt) ATT_ISSUE(j + 2, is);
.Lgq_dma_stub:
	s_or_b64 exec, exec, s[42:43]
	global_load_lds_dwordx4 v[210:211], off
	v_add_u32_e32 v210, 0x1000, v0
	s_mov_b64 s[28:29], 0x10f00
	v_readfirstlane_b32 s40, v210
	v_add_u32_e32 v210, 0x3000, v0
	v_lshl_add_u64 v[2:3], v[2:3], 0, s[28:29]
	s_mov_b32 m0, s40
	s_lshl_b64 s[40:41], s[20:21], 1
	v_readfirstlane_b32 s20, v210
	v_add_u32_e32 v0, 0x4000, v0
	global_load_lds_dwordx4 v[2:3], off
	v_lshl_add_u64 v[2:3], v[104:105], 0, s[40:41]
	s_mov_b32 m0, s20
	v_readfirstlane_b32 s20, v0
	global_load_lds_dwordx4 v[2:3], off
	v_lshl_add_u64 v[2:3], v[108:109], 0, s[40:41]
	s_mov_b32 m0, s20
	s_nop 0
	global_load_lds_dwordx4 v[2:3], off
	s_branch .LBB0_2268

; template <int DK, int QB, bool NA>
; DEVI void attn_item(const AttnArgs& a, unsigned char* smem) {
;     ...
;   for (int j = 0; j < nt; ++j) {
;     if (j + 1 < nt) {
;       if constexpr (DK == 96) asm volatile("s_waitcnt vmcnt(5)" ::: "memory");
;       else                    asm volatile("s_waitcnt vmcnt(4)" ::: "memory");
;     } else {
;       asm volatile("s_waitcnt vmcnt(0)" ::: "memory");
;     }
;     RAW_BARRIER();
;     if (j + 2 < nt) ATT_ISSUE(j + 2, is);
;     is = (is + 1 == S) ? 0 : is + 1;
;     const unsigned cur = lbase + cs * ATT_STAGE;
;     cs = (cs + 1 == S) ? 0 : cs + 1;
;     if (wact) {
;       f32x4 s[4][QB];
; #pragma unroll
;       for (int kb = 0; kb < 4; ++kb)
; #pragma unroll
;         for (int qb = 0; qb < QB; ++qb) s[kb][qb] = (f32x4){0.f, 0.f, 0.f, 0.f};
;       {
;         bf16x8 k0[4], k1[4], k2[4];
;         const unsigned a0 = cur + ka0, a1 = cur + ka1, a2 = cur + kr;
;         k0[0] = ldsr<0>(a0); k0[1] = ldsr<2048>(a0); k0[2] = ldsr<4096>(a0); k0[3] = ldsr<6144>(a0);
;         k1[0] = ldsr<0>(a1); k1[1] = ldsr<2048>(a1); k1[2] = ldsr<4096>(a1); k1[3] = ldsr<6144>(a1);
;         if constexpr (KS == 3) { k2[0] = ldsr<0>(a2); k2[1] = ldsr<1024>(a2); k2[2] = ldsr<2048>(a2); k2[3] = ldsr<3072>(a2); }
;         if constexpr (KS == 3) asm volatile("s_waitcnt lgkmcnt(8)" : "+v"(k0[0]), "+v"(k0[1]), "+v"(k0[2]), "+v"(k0[3]) :: "memory");
;         else                   asm volatile("s_waitcnt lgkmcnt(4)" : "+v"(k0[0]), "+v"(k0[1]), "+v"(k0[2]), "+v"(k0[3]) :: "memory");
;         __builtin_amdgcn_sched_barrier(0);
; #pragma unroll
;         for (int kb = 0; kb < 4; ++kb)
; #pragma unroll
;           for (int qb = 0; qb < QB; ++qb) s[kb][qb] = __builtin_amdgcn_mfma_f32_16x16x32_bf16(k0[kb], qf[qb][0], s[kb][qb], 0, 0, 0);
;         if constexpr (KS == 3) asm volatile("s_waitcnt lgkmcnt(4)" : "+v"(k1[0]), "+v"(k1[1]), "+v"(k1[2]), "+v"(k1[3]) :: "memory");
;         else                   asm volatile("s_waitcnt lgkmcnt(0)" : "+v"(k1[0]), "+v"(k1[1]), "+v"(k1[2]), "+v"(k1[3]) :: "memory");
;         __builtin_amdgcn_sched_barrier(0);
; #pragma unroll
;         for (int kb = 0; kb < 4; ++kb)
; #pragma unroll
;           for (int qb = 0; qb < QB; ++qb) s[kb][qb] = __builtin_amdgcn_mfma_f32_16x16x32_bf16(k1[kb], qf[qb][1], s[kb][qb], 0, 0, 0);
;         if constexpr (KS == 3) {
.LBB0_2314:
	s_add_i32 s42, s42, 1
	s_cmp_lt_u32 s42, s61
	s_cselect_b32 s20, s43, s60
	s_mul_i32 s2, s9, 0x5000
	v_add_u32_e32 v0, s2, v216
	v_mad_u64_u32 v[2:3], s[2:3], s20, v207, v[114:115]
	v_readfirstlane_b32 s2, v0
	v_add_u32_e32 v221, 0x1000, v0
	s_mul_i32 s100, s8, 0x5000
	v_or_b32_e32 v218, s100, v213
	v_or_b32_e32 v219, s100, v214
	v_add_u32_e32 v220, s100, v215
	s_waitcnt vmcnt(5)
	s_mov_b32 m0, s2
	v_readfirstlane_b32 s101, v221
	s_waitcnt lgkmcnt(0)
	s_barrier
	ds_read_b128 v[60:63], v218 offset:0
	ds_read_b128 v[64:67], v218 offset:0x800
	ds_read_b128 v[68:71], v218 offset:0x1000
	ds_read_b128 v[72:75], v218 offset:0x1800
	ds_read_b128 v[76:79], v219 offset:0
	ds_read_b128 v[80:83], v219 offset:0x800
	ds_read_b128 v[84:87], v219 offset:0x1000
	ds_read_b128 v[88:91], v219 offset:0x1800
	ds_read_b128 v[92:95], v220 offset:0
	ds_read_b128 v[96:99], v220 offset:0x400
	ds_read_b128 v[120:123], v220 offset:0x800
	ds_read_b128 v[124:127], v220 offset:0xc00
	s_and_saveexec_b64 s[2:3], s[0:1]
	s_cbranch_execz .Lml_dma_stub
	s_waitcnt lgkmcnt(8)
	s_setprio 1
	v_mfma_f32_16x16x32_bf16 v[100:103], v[60:63], v[24:27], 0
	global_load_lds_dwordx4 v[2:3], off
	v_lshl_add_u64 v[2:3], v[2:3], 0, s[86:87]
	s_mov_b32 m0, s101
	s_waitcnt lgkmcnt(4)
	v_mfma_f32_16x16x32_bf16 v[60:63], v[60:63], v[20:23], 0
	v_add_u32_e32 v221, 0x2000, v0
	global_load_lds_dwordx4 v[2:3], off
	v_mfma_f32_16x16x32_bf16 v[104:107], v[64:67], v[24:27], 0
	v_mad_u64_u32 v[2:3], vcc, s20, v207, v[116:117]
	v_readfirstlane_b32 s101, v221
	v_add_u32_e32 v221, 0x3000, v0
	v_mfma_f32_16x16x32_bf16 v[64:67], v[64:67], v[20:23], 0
	v_lshl_add_u64 v[2:3], v[2:3], 0, s[28:29]
	s_mov_b32 m0, s101
	s_lshl_b64 vcc, s[20:21], 1
	v_mfma_f32_16x16x32_bf16 v[180:183], v[68:71], v[24:27], 0
	v_readfirstlane_b32 s20, v221
	global_load_lds_dwordx4 v[2:3], off
	v_lshl_add_u64 v[2:3], v[112:113], 0, vcc
	v_mfma_f32_16x16x32_bf16 v[68:71], v[68:71], v[20:23], 0
	s_mov_b32 m0, s20
	v_add_u32_e32 v0, 0x4000, v0
	global_load_lds_dwordx4 v[2:3], off
	v_mfma_f32_16x16x32_bf16 v[218:221], v[72:75], v[24:27], 0
	v_lshl_add_u64 v[2:3], v[118:119], 0, vcc
	v_readfirstlane_b32 s101, v0
	s_mov_b32 m0, s101
	v_mfma_f32_16x16x32_bf16 v[72:75], v[72:75], v[20:23], 0
	global_load_lds_dwordx4 v[2:3], off
	v_mfma_f32_16x16x32_bf16 v[100:103], v[76:79], v[16:19], v[100:103]
	s_waitcnt lgkmcnt(0)
	v_mfma_f32_16x16x32_bf16 v[60:63], v[76:79], v[12:15], v[60:63]
	v_mfma_f32_16x16x32_bf16 v[76:79], v[80:83], v[16:19], v[104:107]
	v_mfma_f32_16x16x32_bf16 v[64:67], v[80:83], v[12:15], v[64:67]
	v_mfma_f32_16x16x32_bf16 v[80:83], v[84:87], v[16:19], v[180:183]
	v_mfma_f32_16x16x32_bf16 v[68:71], v[84:87], v[12:15], v[68:71]
	v_mfma_f32_16x16x32_bf16 v[84:87], v[88:91], v[16:19], v[218:221]
	v_mfma_f32_16x16x32_bf16 v[72:75], v[88:91], v[12:15], v[72:75]
	v_mfma_f32_16x16x32_bf16 v[182:185], v[92:95], v[8:11], v[100:103]
	v_add_u32_e32 v0, s100, v209
	v_add_u32_e32 v2, s100, v210
	ds_read_b64 v[88:89], v0 offset:0
	v_mfma_f32_16x16x32_bf16 v[218:221], v[96:99], v[8:11], v[76:79]
	ds_read_b64 v[90:91], v2 offset:0
	s_nop 4
	v_fma_f32 v180, v184, s34, -v110
	v_fma_f32 v181, v185, s34, -v110
	v_pk_fma_f32 v[182:183], v[182:183], s[34:35], v[110:111] op_sel_hi:[1,0,0] neg_lo:[0,0,1] neg_hi:[0,0,1]
	v_mfma_f32_16x16x32_bf16 v[222:225], v[120:123], v[8:11], v[80:83]
	v_add_u32_e32 v3, s100, v211
	v_pk_fma_f32 v[128:129], v[220:221], s[34:35], v[110:111] op_sel_hi:[1,0,0] neg_lo:[0,0,1] neg_hi:[0,0,1]
	v_mfma_f32_16x16x32_bf16 v[226:229], v[124:127], v[8:11], v[84:87]
	ds_read_b64 v[84:85], v0 offset:0x800
	ds_read_b64 v[86:87], v2 offset:0x800
	ds_read_b64 v[80:81], v0 offset:0x1000
	v_mfma_f32_16x16x32_bf16 v[104:107], v[92:95], v[4:7], v[60:63]
	ds_read_b64 v[82:83], v2 offset:0x1000
	ds_read_b64 v[76:77], v0 offset:0x1800
	v_max_f32_e32 v0, v180, v181
	v_mfma_f32_16x16x32_bf16 v[92:95], v[124:127], v[4:7], v[72:75]
	v_fma_f32 v126, v218, s34, -v110
	v_fma_f32 v127, v219, s34, -v110
	v_pk_fma_f32 v[124:125], v[222:223], s[34:35], v[110:111] op_sel_hi:[1,0,0] neg_lo:[0,0,1] neg_hi:[0,0,1]
	v_max3_f32 v0, v182, v183, v0
	v_mfma_f32_16x16x32_bf16 v[100:103], v[96:99], v[4:7], v[64:67]
	v_max_f32_e32 v184, v126, v127
	v_max_f32_e32 v185, v128, v129
	v_add_u32_e32 v62, s100, v212
	v_mfma_f32_16x16x32_bf16 v[96:99], v[120:123], v[4:7], v[68:71]
	s_setprio 0
	v_fma_f32 v122, v224, s34, -v110
	v_fma_f32 v123, v225, s34, -v110
	ds_read_b64 v[78:79], v2 offset:0x1800
	ds_read_b64 v[72:73], v3 offset:0
	ds_read_b64 v[74:75], v62 offset:0
	ds_read_b64 v[68:69], v3 offset:0x800
	ds_read_b64 v[70:71], v62 offset:0x800
	ds_read_b64 v[64:65], v3 offset:0x1000
	ds_read_b64 v[66:67], v62 offset:0x1000
	ds_read_b64 v[60:61], v3 offset:0x1800
	v_pk_fma_f32 v[120:121], v[226:227], s[34:35], v[110:111] op_sel_hi:[1,0,0] neg_lo:[0,0,1] neg_hi:[0,0,1]
	v_pk_fma_f32 v[2:3], v[228:229], s[34:35], v[110:111] op_sel_hi:[1,0,0] neg_lo:[0,0,1] neg_hi:[0,0,1]
	v_max3_f32 v0, v0, v184, v185
	v_max_f32_e32 v184, v124, v125
	v_max_f32_e32 v185, v122, v123
	v_max3_f32 v0, v0, v184, v185
	v_max_f32_e32 v184, v120, v121
	v_max_f32_e32 v185, v2, v3
	v_max3_f32 v0, v0, v184, v185
	s_mov_b32 s20, 0x40c00000
	v_cmp_lt_f32_e32 vcc, s20, v0
	ds_read_b64 v[62:63], v62 offset:0x1800
	s_cbranch_vccz .LBB0_2317
	v_mov_b32_e32 v184, v0
	s_nop 1
	v_permlane16_swap_b32_e32 v0, v184
	v_max_f32_e32 v184, v184, v184
	v_max_f32_e32 v0, v0, v0
	v_max_f32_e32 v0, v0, v184
	v_mov_b32_e32 v184, v0
	s_nop 1
	v_permlane32_swap_b32_e32 v0, v184
	v_max3_f32 v0, v0, v184, 0
	v_exp_f32_e64 v184, -v0
	v_pk_add_f32 v[182:183], v[182:183], v[0:1] op_sel_hi:[1,0] neg_lo:[0,1] neg_hi:[0,1]
	v_pk_add_f32 v[180:181], v[180:181], v[0:1] op_sel_hi:[1,0] neg_lo:[0,1] neg_hi:[0,1]
	v_pk_add_f32 v[126:127], v[126:127], v[0:1] op_sel_hi:[1,0] neg_lo:[0,1] neg_hi:[0,1]
	v_pk_add_f32 v[128:129], v[128:129], v[0:1] op_sel_hi:[1,0] neg_lo:[0,1] neg_hi:[0,1]
	v_pk_add_f32 v[124:125], v[124:125], v[0:1] op_sel_hi:[1,0] neg_lo:[0,1] neg_hi:[0,1]
	v_pk_add_f32 v[122:123], v[122:123], v[0:1] op_sel_hi:[1,0] neg_lo:[0,1] neg_hi:[0,1]
	v_pk_add_f32 v[120:121], v[120:121], v[0:1] op_sel_hi:[1,0] neg_lo:[0,1] neg_hi:[0,1]
	v_pk_add_f32 v[2:3], v[2:3], v[0:1] op_sel_hi:[1,0] neg_lo:[0,1] neg_hi:[0,1]
	v_add_f32_e32 v110, v110, v0
	v_mul_f32_e32 v109, v109, v184
	v_pk_mul_f32 v[58:59], v[58:59], v[184:185] op_sel_hi:[1,0]
	v_pk_mul_f32 v[56:57], v[56:57], v[184:185] op_sel_hi:[1,0]
	v_pk_mul_f32 v[50:51], v[50:51], v[184:185] op_sel_hi:[1,0]
	v_pk_mul_f32 v[48:49], v[48:49], v[184:185] op_sel_hi:[1,0]
	v_pk_mul_f32 v[42:43], v[42:43], v[184:185] op_sel_hi:[1,0]
	v_pk_mul_f32 v[40:41], v[40:41], v[184:185] op_sel_hi:[1,0]
	v_pk_mul_f32 v[34:35], v[34:35], v[184:185] op_sel_hi:[1,0]
	v_pk_mul_f32 v[32:33], v[32:33], v[184:185] op_sel_hi:[1,0]

; template <int DK, int QB, bool NA>
; DEVI void attn_item(const AttnArgs& a, unsigned char* smem) {
;     ...
;     if (j + 2 < nt) ATT_ISSUE(j + 2, is);
.Lml_dma_stub:
	s_or_b64 exec, exec, s[2:3]
	global_load_lds_dwordx4 v[2:3], off
	v_lshl_add_u64 v[2:3], v[2:3], 0, s[86:87]
	s_mov_b32 m0, s101
	v_add_u32_e32 v221, 0x2000, v0
	global_load_lds_dwordx4 v[2:3], off
	v_mad_u64_u32 v[2:3], vcc, s20, v207, v[116:117]
	v_readfirstlane_b32 s101, v221
	v_add_u32_e32 v221, 0x3000, v0
	v_lshl_add_u64 v[2:3], v[2:3], 0, s[28:29]
	s_mov_b32 m0, s101
	s_lshl_b64 vcc, s[20:21], 1
	v_readfirstlane_b32 s20, v221
	global_load_lds_dwordx4 v[2:3], off
	v_lshl_add_u64 v[2:3], v[112:113], 0, vcc
	s_mov_b32 m0, s20
	v_add_u32_e32 v0, 0x4000, v0
	global_load_lds_dwordx4 v[2:3], off
	v_lshl_add_u64 v[2:3], v[118:119], 0, vcc
	v_readfirstlane_b32 s101, v0
	s_mov_b32 m0, s101
	s_nop 0
	global_load_lds_dwordx4 v[2:3], off
	s_branch .LBB0_2313
